# C loop unrolled x3 over the LDS tile buffers (immediate buffer offsets, no rotation) and SGPR-base K/V tile loads; rest as v24
# speedup vs baseline: 1.0049x; 1.0034x over previous
; template <int MODE>
; DI void attn_unit(unsigned char* lds, const AttnParams& ap, int b, int h, int qb, int tid) {
;     ...
;   const int wave = tid >> 6, lane = tid & 63, r32 = lane & 31, hi = lane >> 5, bh = b * 4 + h;
;   constexpr int qcol0 = (MODE == 0) ? C_AQ : (MODE == 1) ? C_CQ : C_DQ, kcol0 = (MODE == 0) ? C_AK : (MODE == 1) ? C_CK : C_DK, ycol0 = (MODE == 0) ? 0 : (MODE == 1) ? 512 : 768;
;   const bf16_t* Vt = ap.Vt + (size_t)((MODE == 0) ? 0 : (MODE == 1) ? 2 : 3) * T_ * 256;
;   const size_t tokb = (size_t)b * SEQ;
;   const int qpos = qb * 256 + wave * 32 + r32, cw = qb * 4 + (wave >> 1);
;   bf16x8 qf[4];
;   { const bf16_t* qp = ap.P + (tokb + qpos) * PLD + qcol0 + h * 64 + 8 * hi;
; #pragma unroll
;     for (int ks = 0; ks < 4; ++ks) qf[ks] = *(const bf16x8*)(qp + 16 * ks); }
;   bf16_t* Ks0 = (bf16_t*)lds; bf16_t* Vs0 = Ks0 + NCH * 64 * 72; volatile int* flags = (volatile int*)(lds + 2 * NCH * 64 * 72 * 2);
;   const int jhi = 4 * qb + 3, jlo = (MODE == 0) ? ((4 * qb - 8 > 0) ? 4 * qb - 8 : 0) : 0, ntiles = jhi - jlo + 1;
;   const int lrow = tid >> 3, lch = tid & 7;
;   const bf16_t* kg = ap.P + (tokb + lrow) * PLD + kcol0 + h * 64 + 8 * lch;
;   const bf16_t* vg = Vt + (size_t)bh * 256 * 4096 + lrow * 64 + 8 * lch;
;   const int j0 = (MODE == 2) ? jhi : jlo;
;   u32x4 kreg[NCH], vreg[NCH];
; #pragma unroll
;   for (int c = 0; c < NCH; ++c) { const int jc = (MODE == 2) ? j0 - c : j0 + c; kreg[c] = *(const u32x4*)(kg + (size_t)jc * 64 * PLD); vreg[c] = *(const u32x4*)(vg + (size_t)jc * 4096); }
;   f32x16 O0[2], O1[2]; float l0 = 0.f, l1 = 0.f, cum = 0.f;
; #pragma unroll
;   for (int eb = 0; eb < 2; ++eb) { O0[eb] = splat16(0.f); O1[eb] = splat16(0.f); }
;   bool wdone = false;
;   if (MODE == 2 && D_EARLY) { if (tid < 8) flags[tid] = 0; }
;   for (int n = 0; n < ntiles; n += NCH) {
;     const int jb = (MODE == 2) ? jhi - n : jlo + n;
;     __syncthreads();
;     if (MODE == 2 && D_EARLY) { int alld = 1;
; #pragma unroll
;       for (int w = 0; w < 8; ++w) alld &= flags[w];
;       if (alld) break; }
; #pragma unroll
;     for (int c = 0; c < NCH; ++c) { *(u32x4*)(Ks0 + (c * 64 + lrow) * 72 + 8 * lch) = kreg[c]; *(u32x4*)(Vs0 + (c * 64 + lrow) * 72 + 8 * lch) = vreg[c]; }
;     __syncthreads();
;     if (n + NCH < ntiles) {
; #pragma unroll
.LBB0_845:
	v_readlane_b32 s0, v255, 51
	v_readlane_b32 s1, v255, 52
	s_andn2_saveexec_b64 s[6:7], s[0:1]
	s_cbranch_execz .LBB0_853
	v_mov_b32_e32 v1, v156
	v_readlane_b32 s0, v255, 25
	v_ashrrev_i32_e32 v2, 1, v1
	v_and_b32_e32 v2, 0xffffffe0, v2
	v_and_b32_e32 v7, 31, v1
	v_lshl_add_u32 v2, v0, 8, v2
	v_or_b32_e32 v2, v2, v7
	v_lshlrev_b32_e32 v32, 14, v4
	v_ashrrev_i32_e32 v3, 31, v2
	v_readlane_b32 s1, v255, 26
	v_lshl_add_u64 v[134:135], v[2:3], 0, v[32:33]
	v_bfe_u32 v47, v1, 5, 1
	v_mov_b64_e32 v[2:3], s[0:1]
	v_mad_u64_u32 v[8:9], s[0:1], v134, s82, v[2:3]
	v_mad_i32_i24 v9, v135, s82, v9
	v_lshlrev_b32_e32 v10, 7, v5
	v_mov_b32_e32 v11, v33
	v_lshl_add_u64 v[8:9], v[8:9], 0, v[10:11]
	v_lshlrev_b32_e32 v132, 4, v47
	v_mov_b32_e32 v133, v33
	v_lshl_add_u64 v[8:9], v[8:9], 0, v[132:133]
	v_ashrrev_i32_e32 v14, 3, v1
	global_load_dwordx4 v[112:115], v[8:9], off offset:3584
	global_load_dwordx4 v[42:45], v[8:9], off offset:3616
	global_load_dwordx4 v[38:41], v[8:9], off offset:3648
	global_load_dwordx4 v[34:37], v[8:9], off offset:3680
	v_add_u32_e32 v8, v14, v32
	v_mad_i64_i32 v[2:3], s[0:1], v8, s82, v[2:3]
	v_lshlrev_b32_e32 v8, 4, v1
	v_and_b32_e32 v32, 0x70, v8
	v_lshlrev_b32_e32 v8, 21, v5
	v_readlane_b32 s0, v255, 41
	v_lshl_add_u64 v[2:3], v[2:3], 0, v[10:11]
	v_lshl_or_b32 v8, v4, 23, v8
	v_mov_b32_e32 v9, v33
	v_readlane_b32 s1, v255, 42
	v_lshlrev_b32_e32 v12, 6, v14
	v_lshl_add_u64 v[2:3], v[2:3], 0, v[32:33]
	v_lshl_add_u64 v[10:11], s[0:1], 0, v[8:9]
	v_ashrrev_i32_e32 v13, 31, v12
	s_movk_i32 s0, 0x1000
	v_lshlrev_b64 v[12:13], 1, v[12:13]
	v_add_co_u32_e32 v2, vcc, s0, v2
	v_lshl_add_u64 v[10:11], v[10:11], 0, v[12:13]
	s_nop 0
	v_addc_co_u32_e32 v3, vcc, 0, v3, vcc
	v_lshl_add_u64 v[10:11], v[10:11], 0, v[32:33]
	global_load_dwordx4 v[120:123], v[2:3], off
	global_load_dwordx4 v[116:119], v[10:11], off
	v_ashrrev_i32_e32 v157, 7, v1
	v_lshlrev_b32_e32 v0, 2, v0
	v_mul_lo_u32 v1, v14, s68
	v_or_b32_e32 v12, v12, v32
	v_readlane_b32 s0, v255, 47
	v_add_u32_e32 v191, v157, v0
	v_add3_u32 v190, 0, v32, v1
	v_or_b32_e32 v192, 3, v0
	v_lshl_add_u64 v[0:1], v[12:13], 0, v[8:9]
	v_readlane_b32 s1, v255, 48
	v_add_u16_e32 v2, -1, v6
	v_and_b32_e32 v2, 3, v2
	v_lshl_add_u64 v[136:137], s[0:1], 0, v[0:1]
	v_mad_i64_i32 v[0:1], s[0:1], v14, s82, 0
	s_mov_b32 s0, 0x6880000
	s_nop 0
	v_mad_u64_u32 v[0:1], s[0:1], v4, s0, v[0:1]
	v_lshlrev_b32_e32 v2, 7, v2
	v_mov_b32_e32 v3, v33
	v_lshl_add_u64 v[0:1], v[0:1], 0, v[2:3]
	v_readlane_b32 s0, v255, 49
	v_lshl_add_u64 v[0:1], v[0:1], 0, v[32:33]
	v_readlane_b32 s1, v255, 50
	v_mov_b32_e32 v14, v33
	v_mov_b32_e32 v15, v33
	v_lshlrev_b32_e32 v46, 6, v5
	v_mul_u32_u24_e32 v155, 0x90, v7
	v_lshl_add_u64 v[138:139], s[0:1], 0, v[0:1]
	v_mov_b32_e32 v32, v33
	v_mov_b32_e32 v0, v33
	v_mov_b32_e32 v1, v33
	v_mov_b32_e32 v2, v33
	v_mov_b32_e32 v4, v33
	v_mov_b32_e32 v5, v33
	v_mov_b32_e32 v6, v33
	v_mov_b32_e32 v7, v33
	v_mov_b32_e32 v8, v33
	v_mov_b32_e32 v10, v33
	v_mov_b32_e32 v11, v33
	v_mov_b32_e32 v12, v33
	v_mov_b32_e32 v13, v33
	v_mov_b64_e32 v[78:79], v[14:15]
	v_mov_b64_e32 v[30:31], v[14:15]
	v_mov_b64_e32 v[94:95], v[14:15]
	s_mov_b32 s4, 0
	v_add_u32_e32 v133, 0, v132
	s_mov_b64 s[0:1], 0
	v_mov_b64_e32 v[76:77], v[12:13]
	v_mov_b64_e32 v[74:75], v[10:11]
	v_mov_b64_e32 v[72:73], v[8:9]
	v_mov_b64_e32 v[70:71], v[6:7]
	v_mov_b64_e32 v[68:69], v[4:5]
	v_mov_b64_e32 v[66:67], v[2:3]
	v_mov_b64_e32 v[64:65], v[0:1]
	v_mov_b64_e32 v[28:29], v[12:13]
	v_mov_b64_e32 v[26:27], v[10:11]
	v_mov_b64_e32 v[24:25], v[8:9]
	v_mov_b64_e32 v[22:23], v[6:7]
	v_mov_b64_e32 v[20:21], v[4:5]
	v_mov_b64_e32 v[18:19], v[2:3]
	v_mov_b64_e32 v[16:17], v[0:1]
	v_mov_b64_e32 v[92:93], v[12:13]
	v_mov_b64_e32 v[90:91], v[10:11]
	v_mov_b64_e32 v[88:89], v[8:9]
	v_mov_b64_e32 v[86:87], v[6:7]
	v_mov_b64_e32 v[84:85], v[4:5]
	v_mov_b64_e32 v[82:83], v[2:3]
	v_mov_b64_e32 v[80:81], v[0:1]
	v_mov_b64_e32 v[140:141], v[32:33]
	v_readfirstlane_b32 s5, v191
	v_readfirstlane_b32 s8, v192
	v_readfirstlane_b32 s2, v138
	v_readfirstlane_b32 s3, v139
	v_readfirstlane_b32 s10, v136
	v_readfirstlane_b32 s11, v137
	v_add_u32_e32 v133, v133, v155
	s_nop 1
	v_subrev_u32_e32 v32, s2, v138
	v_subrev_u32_e32 v157, s10, v136
	s_nop 3
	global_load_dwordx4 v[96:99], v32, s[2:3]
	global_load_dwordx4 v[100:103], v157, s[10:11]
	s_add_u32 s2, s2, 0x68800
	s_addc_u32 s3, s3, 0
	s_add_u32 s10, s10, 0x2000
	s_addc_u32 s11, s11, 0
	s_waitcnt vmcnt(2)
	ds_write_b128 v190, v[120:123]
	ds_write_b128 v190, v[116:119] offset:9216
	s_waitcnt vmcnt(0)
	ds_write_b128 v190, v[96:99] offset:18432
	ds_write_b128 v190, v[100:103] offset:27648
	s_waitcnt lgkmcnt(0)
	s_barrier
	ds_read_b128 v[166:169], v133
	ds_read_b128 v[170:173], v133 offset:32
	v_mov_b32_e32 v158, 0
	v_mov_b32_e32 v159, 0
	v_mov_b32_e32 v160, 0
	v_mov_b32_e32 v161, 0
	v_mov_b32_e32 v162, 0
	v_mov_b32_e32 v163, 0
	v_mov_b32_e32 v164, 0
	v_mov_b32_e32 v165, 0
	v_mov_b32_e32 v150, 0
	v_mov_b32_e32 v151, 0
	s_mov_b32 s4, 0
	s_waitcnt lgkmcnt(0)
	v_mfma_f32_32x32x16_bf16 v[96:111], v[166:169], v[112:115], v[48:63]
	v_mfma_f32_32x32x16_bf16 v[96:111], v[170:173], v[42:45], v[96:111]
	ds_read_b128 v[166:169], v133 offset:64
	ds_read_b128 v[170:173], v133 offset:96
	v_mov_b32_e32 v174, 0
	v_mov_b32_e32 v175, 0
	v_mov_b32_e32 v176, 0
	v_mov_b32_e32 v177, 0
	v_mov_b32_e32 v178, 0
	v_mov_b32_e32 v179, 0
	v_mov_b32_e32 v180, 0
	v_mov_b32_e32 v181, 0
	v_mov_b32_e32 v182, 0
	v_mov_b32_e32 v183, 0
	v_mov_b32_e32 v184, 0
	v_mov_b32_e32 v185, 0
	v_mov_b32_e32 v186, 0
	v_mov_b32_e32 v187, 0
	v_mov_b32_e32 v188, 0
	v_mov_b32_e32 v189, 0
; DI float ex2(float x) { return __builtin_amdgcn_exp2f(x); }
; #define MFMA32(a, b, c) __builtin_amdgcn_mfma_f32_32x32x16_bf16((a), (b), (c), 0, 0, 0)
; template <int MODE>
; DI void attn_unit(unsigned char* lds, const AttnParams& ap, int b, int h, int qb, int tid) {
;     ...
;     for (int c = 0; c < NCH; ++c) { *(u32x4*)(Ks0 + (c * 64 + lrow) * 72 + 8 * lch) = kreg[c]; *(u32x4*)(Vs0 + (c * 64 + lrow) * 72 + 8 * lch) = vreg[c]; }
;     __syncthreads();
;     if (n + NCH < ntiles) {
; #pragma unroll
;       for (int c = 0; c < NCH; ++c) { const int jn = (MODE == 2) ? jb - NCH - c : jb + NCH + c; kreg[c] = *(const u32x4*)(kg + (size_t)jn * 64 * PLD); vreg[c] = *(const u32x4*)(vg + (size_t)jn * 4096); } }
; #pragma unroll
;     for (int c = 0; c < NCH; ++c) {
;     const int j = (MODE == 2) ? jb - c : jb + c;
;     const bf16_t* Ks = Ks0 + c * 64 * 72; const bf16_t* Vs = Vs0 + c * 64 * 72;
;     const bool active = (j <= cw) && (MODE != 0 || j >= cw - 8);
;     if (!active) continue;
;     if (MODE == 2 && D_EARLY && wdone) continue;
;     if (MODE == 1) {
; #pragma unroll
;       for (int kh = 0; kh < 2; ++kh) {
;         const bf16_t* kb = Ks + (32 * kh + r32) * 72 + 8 * hi;
;         bf16x8 p0[2], p1[2];
;         { f32x16 s0 = splat16(ap.negM);
;           s0 = MFMA32(*(const bf16x8*)(kb), qf[0], s0); s0 = MFMA32(*(const bf16x8*)(kb + 16), qf[1], s0);
; #pragma unroll
;           for (int i = 0; i < 16; ++i) { s0[i] = ex2(s0[i]); l0 += s0[i]; }
;           p0[0] = pack8(s0, 0); p0[1] = pack8(s0, 1); }
;         { f32x16 s1 = splat16(ap.negM);
;           s1 = MFMA32(*(const bf16x8*)(kb + 32), qf[2], s1); s1 = MFMA32(*(const bf16x8*)(kb + 48), qf[3], s1);
; #pragma unroll
;           for (int i = 0; i < 16; ++i) { s1[i] = ex2(s1[i]); l1 += s1[i]; }
;           p1[0] = pack8(s1, 0); p1[1] = pack8(s1, 1); }
; #pragma unroll
;         for (int kk = 0; kk < 2; ++kk) {
; #pragma unroll
;           for (int eb = 0; eb < 2; ++eb) { const bf16_t* vb = Vs + (32 * eb + r32) * 72 + 32 * kh + 16 * kk + 8 * hi; const bf16x8 vf = *(const bf16x8*)vb;
;             O0[eb] = MFMA32(vf, p0[kk], O0[eb]); O1[eb] = MFMA32(vf, p1[kk], O1[eb]); } }
;       }
.Lc_tile_ph0:
	global_load_dwordx4 v[204:207], v32, s[2:3]
	global_load_dwordx4 v[142:145], v157, s[10:11]
	s_add_u32 s2, s2, 0x68800
	s_addc_u32 s3, s3, 0
	s_add_u32 s10, s10, 0x2000
	s_addc_u32 s11, s11, 0
	s_waitcnt lgkmcnt(0)
	v_mfma_f32_32x32x16_bf16 v[116:131], v[166:169], v[38:41], v[48:63]
	v_exp_f32_e32 v96, v96
	v_exp_f32_e32 v97, v97
	v_exp_f32_e32 v98, v98
	v_exp_f32_e32 v99, v99
	v_mfma_f32_32x32x16_bf16 v[116:131], v[170:173], v[34:37], v[116:131]
	v_exp_f32_e32 v100, v100
	v_exp_f32_e32 v101, v101
	v_exp_f32_e32 v102, v102
	v_exp_f32_e32 v103, v103
	ds_read_b128 v[166:169], v133 offset:4608
	ds_read_b128 v[170:173], v133 offset:4640
	v_mfma_f32_32x32x16_bf16 v[80:95], v[174:177], v[158:161], v[80:95]
	v_exp_f32_e32 v104, v104
	v_exp_f32_e32 v105, v105
	v_add_f32_e32 v141, v141, v96
	v_add_f32_e32 v150, v150, v97
	v_add_f32_e32 v141, v141, v98
	v_add_f32_e32 v150, v150, v99
	v_mfma_f32_32x32x16_bf16 v[16:31], v[182:185], v[158:161], v[16:31]
	v_exp_f32_e32 v106, v106
	v_exp_f32_e32 v107, v107
	v_cvt_pk_bf16_f32 v158, v96, v97
	v_cvt_pk_bf16_f32 v159, v98, v99
	v_add_f32_e32 v141, v141, v100
	v_add_f32_e32 v150, v150, v101
	v_mfma_f32_32x32x16_bf16 v[80:95], v[178:181], v[162:165], v[80:95]
	v_exp_f32_e32 v108, v108
	v_exp_f32_e32 v109, v109
	v_cvt_pk_bf16_f32 v160, v100, v101
	v_cvt_pk_bf16_f32 v161, v102, v103
	v_add_f32_e32 v141, v141, v102
	v_add_f32_e32 v150, v150, v103
	v_mfma_f32_32x32x16_bf16 v[16:31], v[186:189], v[162:165], v[16:31]
	ds_read_b128 v[174:177], v133 offset:9216
	ds_read_b128 v[178:181], v133 offset:9248
	ds_read_b128 v[182:185], v133 offset:13824
	ds_read_b128 v[186:189], v133 offset:13856
	v_exp_f32_e32 v110, v110
	v_exp_f32_e32 v111, v111
	v_add_f32_e32 v141, v141, v104
	v_add_f32_e32 v150, v150, v105
	v_add_f32_e32 v141, v141, v106
	v_add_f32_e32 v150, v150, v107
	v_add_f32_e32 v141, v141, v108
	v_add_f32_e32 v150, v150, v109
	v_cvt_pk_bf16_f32 v162, v104, v105
	v_cvt_pk_bf16_f32 v163, v106, v107
	v_cvt_pk_bf16_f32 v164, v108, v109
	v_add_f32_e32 v141, v141, v110
	v_add_f32_e32 v150, v150, v111
	v_cvt_pk_bf16_f32 v165, v110, v111
	s_waitcnt lgkmcnt(0)
	v_mfma_f32_32x32x16_bf16 v[96:111], v[166:169], v[112:115], v[48:63]
	v_exp_f32_e32 v116, v116
	v_exp_f32_e32 v117, v117
	v_exp_f32_e32 v118, v118
	v_exp_f32_e32 v119, v119
	v_mfma_f32_32x32x16_bf16 v[96:111], v[170:173], v[42:45], v[96:111]
	v_exp_f32_e32 v120, v120
	v_exp_f32_e32 v121, v121
	v_exp_f32_e32 v122, v122
	v_exp_f32_e32 v123, v123
	ds_read_b128 v[166:169], v133 offset:4672
	ds_read_b128 v[170:173], v133 offset:4704
	v_mfma_f32_32x32x16_bf16 v[64:79], v[174:177], v[158:161], v[64:79]
	v_exp_f32_e32 v124, v124
	v_exp_f32_e32 v125, v125
	v_add_f32_e32 v140, v140, v116
	v_add_f32_e32 v151, v151, v117
	v_add_f32_e32 v140, v140, v118
	v_add_f32_e32 v151, v151, v119
	v_mfma_f32_32x32x16_bf16 v[0:15], v[182:185], v[158:161], v[0:15]
	v_exp_f32_e32 v126, v126
	v_exp_f32_e32 v127, v127
	v_cvt_pk_bf16_f32 v158, v116, v117
	v_cvt_pk_bf16_f32 v159, v118, v119
	v_add_f32_e32 v140, v140, v120
	v_add_f32_e32 v151, v151, v121
	v_mfma_f32_32x32x16_bf16 v[64:79], v[178:181], v[162:165], v[64:79]
	v_exp_f32_e32 v128, v128
	v_exp_f32_e32 v129, v129
	v_cvt_pk_bf16_f32 v160, v120, v121
	v_cvt_pk_bf16_f32 v161, v122, v123
	v_add_f32_e32 v140, v140, v122
	v_add_f32_e32 v151, v151, v123
	v_mfma_f32_32x32x16_bf16 v[0:15], v[186:189], v[162:165], v[0:15]
	v_exp_f32_e32 v130, v130
	v_exp_f32_e32 v131, v131
	v_add_f32_e32 v140, v140, v124
	v_add_f32_e32 v151, v151, v125
	v_add_f32_e32 v140, v140, v126
	v_add_f32_e32 v151, v151, v127
	v_add_f32_e32 v140, v140, v128
	v_add_f32_e32 v151, v151, v129
	v_cvt_pk_bf16_f32 v162, v124, v125
	v_cvt_pk_bf16_f32 v163, v126, v127
	v_cvt_pk_bf16_f32 v164, v128, v129
	v_add_f32_e32 v140, v140, v130
	v_add_f32_e32 v151, v151, v131
	v_cvt_pk_bf16_f32 v165, v130, v131
	s_waitcnt lgkmcnt(0)
	v_mfma_f32_32x32x16_bf16 v[116:131], v[166:169], v[38:41], v[48:63]
	v_exp_f32_e32 v96, v96
	v_exp_f32_e32 v97, v97
	v_exp_f32_e32 v98, v98
	v_exp_f32_e32 v99, v99
	v_mfma_f32_32x32x16_bf16 v[116:131], v[170:173], v[34:37], v[116:131]
	v_exp_f32_e32 v100, v100
	v_exp_f32_e32 v101, v101
	v_exp_f32_e32 v102, v102
	v_exp_f32_e32 v103, v103
	ds_read_b128 v[166:169], v133 offset:18432
	ds_read_b128 v[170:173], v133 offset:18464
	v_mfma_f32_32x32x16_bf16 v[80:95], v[174:177], v[158:161], v[80:95]
	v_exp_f32_e32 v104, v104
	v_exp_f32_e32 v105, v105
	v_add_f32_e32 v141, v141, v96
	v_add_f32_e32 v150, v150, v97
	v_add_f32_e32 v141, v141, v98
	v_add_f32_e32 v150, v150, v99
	v_mfma_f32_32x32x16_bf16 v[16:31], v[182:185], v[158:161], v[16:31]
	v_exp_f32_e32 v106, v106
	v_exp_f32_e32 v107, v107
	v_cvt_pk_bf16_f32 v158, v96, v97
	v_cvt_pk_bf16_f32 v159, v98, v99
	v_add_f32_e32 v141, v141, v100
	v_add_f32_e32 v150, v150, v101
	v_mfma_f32_32x32x16_bf16 v[80:95], v[178:181], v[162:165], v[80:95]
	v_exp_f32_e32 v108, v108
	v_exp_f32_e32 v109, v109
	v_cvt_pk_bf16_f32 v160, v100, v101
	v_cvt_pk_bf16_f32 v161, v102, v103
	v_add_f32_e32 v141, v141, v102
	v_add_f32_e32 v150, v150, v103
	v_mfma_f32_32x32x16_bf16 v[16:31], v[186:189], v[162:165], v[16:31]
	ds_read_b128 v[174:177], v133 offset:9280
	ds_read_b128 v[178:181], v133 offset:9312
	ds_read_b128 v[182:185], v133 offset:13888
	ds_read_b128 v[186:189], v133 offset:13920
	v_exp_f32_e32 v110, v110
	v_exp_f32_e32 v111, v111
	v_add_f32_e32 v141, v141, v104
	v_add_f32_e32 v150, v150, v105
	v_add_f32_e32 v141, v141, v106
	v_add_f32_e32 v150, v150, v107
	v_add_f32_e32 v141, v141, v108
	v_add_f32_e32 v150, v150, v109
	v_cvt_pk_bf16_f32 v162, v104, v105
	v_cvt_pk_bf16_f32 v163, v106, v107
	v_cvt_pk_bf16_f32 v164, v108, v109
	v_add_f32_e32 v141, v141, v110
	v_add_f32_e32 v150, v150, v111
	v_cvt_pk_bf16_f32 v165, v110, v111
	s_waitcnt lgkmcnt(0)
; DI float ex2(float x) { return __builtin_amdgcn_exp2f(x); }
; #define MFMA32(a, b, c) __builtin_amdgcn_mfma_f32_32x32x16_bf16((a), (b), (c), 0, 0, 0)
; template <int MODE>
; DI void attn_unit(unsigned char* lds, const AttnParams& ap, int b, int h, int qb, int tid) {
;     ...
;     for (int c = 0; c < NCH; ++c) { *(u32x4*)(Ks0 + (c * 64 + lrow) * 72 + 8 * lch) = kreg[c]; *(u32x4*)(Vs0 + (c * 64 + lrow) * 72 + 8 * lch) = vreg[c]; }
;     __syncthreads();
;     if (n + NCH < ntiles) {
; #pragma unroll
;       for (int c = 0; c < NCH; ++c) { const int jn = (MODE == 2) ? jb - NCH - c : jb + NCH + c; kreg[c] = *(const u32x4*)(kg + (size_t)jn * 64 * PLD); vreg[c] = *(const u32x4*)(vg + (size_t)jn * 4096); } }
; #pragma unroll
;     for (int c = 0; c < NCH; ++c) {
;     const int j = (MODE == 2) ? jb - c : jb + c;
;     const bf16_t* Ks = Ks0 + c * 64 * 72; const bf16_t* Vs = Vs0 + c * 64 * 72;
;     const bool active = (j <= cw) && (MODE != 0 || j >= cw - 8);
;     if (!active) continue;
;     if (MODE == 2 && D_EARLY && wdone) continue;
;     if (MODE == 1) {
; #pragma unroll
;       for (int kh = 0; kh < 2; ++kh) {
;         const bf16_t* kb = Ks + (32 * kh + r32) * 72 + 8 * hi;
;         bf16x8 p0[2], p1[2];
;         { f32x16 s0 = splat16(ap.negM);
;           s0 = MFMA32(*(const bf16x8*)(kb), qf[0], s0); s0 = MFMA32(*(const bf16x8*)(kb + 16), qf[1], s0);
; #pragma unroll
;           for (int i = 0; i < 16; ++i) { s0[i] = ex2(s0[i]); l0 += s0[i]; }
;           p0[0] = pack8(s0, 0); p0[1] = pack8(s0, 1); }
;         { f32x16 s1 = splat16(ap.negM);
;           s1 = MFMA32(*(const bf16x8*)(kb + 32), qf[2], s1); s1 = MFMA32(*(const bf16x8*)(kb + 48), qf[3], s1);
; #pragma unroll
;           for (int i = 0; i < 16; ++i) { s1[i] = ex2(s1[i]); l1 += s1[i]; }
;           p1[0] = pack8(s1, 0); p1[1] = pack8(s1, 1); }
; #pragma unroll
;         for (int kk = 0; kk < 2; ++kk) {
; #pragma unroll
;           for (int eb = 0; eb < 2; ++eb) { const bf16_t* vb = Vs + (32 * eb + r32) * 72 + 32 * kh + 16 * kk + 8 * hi; const bf16x8 vf = *(const bf16x8*)vb;
;             O0[eb] = MFMA32(vf, p0[kk], O0[eb]); O1[eb] = MFMA32(vf, p1[kk], O1[eb]); } }
;       }
	v_mfma_f32_32x32x16_bf16 v[96:111], v[166:169], v[112:115], v[48:63]
	v_exp_f32_e32 v116, v116
	v_exp_f32_e32 v117, v117
	v_exp_f32_e32 v118, v118
	v_exp_f32_e32 v119, v119
	v_mfma_f32_32x32x16_bf16 v[96:111], v[170:173], v[42:45], v[96:111]
	v_exp_f32_e32 v120, v120
	v_exp_f32_e32 v121, v121
	v_exp_f32_e32 v122, v122
	v_exp_f32_e32 v123, v123
	ds_read_b128 v[166:169], v133 offset:18496
	ds_read_b128 v[170:173], v133 offset:18528
	v_mfma_f32_32x32x16_bf16 v[64:79], v[174:177], v[158:161], v[64:79]
	v_exp_f32_e32 v124, v124
	v_exp_f32_e32 v125, v125
	v_add_f32_e32 v140, v140, v116
	v_add_f32_e32 v151, v151, v117
	v_add_f32_e32 v140, v140, v118
	v_add_f32_e32 v151, v151, v119
	v_mfma_f32_32x32x16_bf16 v[0:15], v[182:185], v[158:161], v[0:15]
	v_exp_f32_e32 v126, v126
	v_exp_f32_e32 v127, v127
	v_cvt_pk_bf16_f32 v158, v116, v117
	v_cvt_pk_bf16_f32 v159, v118, v119
	v_add_f32_e32 v140, v140, v120
	v_add_f32_e32 v151, v151, v121
	v_mfma_f32_32x32x16_bf16 v[64:79], v[178:181], v[162:165], v[64:79]
	v_exp_f32_e32 v128, v128
	v_exp_f32_e32 v129, v129
	v_cvt_pk_bf16_f32 v160, v120, v121
	v_cvt_pk_bf16_f32 v161, v122, v123
	v_add_f32_e32 v140, v140, v122
	v_add_f32_e32 v151, v151, v123
	v_mfma_f32_32x32x16_bf16 v[0:15], v[186:189], v[162:165], v[0:15]
	v_exp_f32_e32 v130, v130
	v_exp_f32_e32 v131, v131
	v_add_f32_e32 v140, v140, v124
	v_add_f32_e32 v151, v151, v125
	v_add_f32_e32 v140, v140, v126
	v_add_f32_e32 v151, v151, v127
	v_add_f32_e32 v140, v140, v128
	v_add_f32_e32 v151, v151, v129
	v_cvt_pk_bf16_f32 v162, v124, v125
	v_cvt_pk_bf16_f32 v163, v126, v127
	v_cvt_pk_bf16_f32 v164, v128, v129
	v_add_f32_e32 v140, v140, v130
	v_add_f32_e32 v151, v151, v131
	v_cvt_pk_bf16_f32 v165, v130, v131
	s_waitcnt vmcnt(0)
	ds_write_b128 v190, v[204:207] offset:36864
	ds_write_b128 v190, v[142:145] offset:46080
	s_add_i32 s4, s4, 1
	s_waitcnt lgkmcnt(0)
	s_barrier
	s_nop 0
	s_barrier
	s_cmp_le_u32 s4, s5
	s_cbranch_scc1 .Lc_tile_ph1
	s_mov_b32 s9, 1
	s_branch .Lc_drain
.Lc_tile_ph1:
	global_load_dwordx4 v[204:207], v32, s[2:3]
	global_load_dwordx4 v[142:145], v157, s[10:11]
	s_add_u32 s2, s2, 0x68800
	s_addc_u32 s3, s3, 0
	s_add_u32 s10, s10, 0x2000
	s_addc_u32 s11, s11, 0
	s_waitcnt lgkmcnt(0)
	v_mfma_f32_32x32x16_bf16 v[116:131], v[166:169], v[38:41], v[48:63]
	v_exp_f32_e32 v96, v96
	v_exp_f32_e32 v97, v97
	v_exp_f32_e32 v98, v98
	v_exp_f32_e32 v99, v99
	v_mfma_f32_32x32x16_bf16 v[116:131], v[170:173], v[34:37], v[116:131]
	v_exp_f32_e32 v100, v100
	v_exp_f32_e32 v101, v101
	v_exp_f32_e32 v102, v102
	v_exp_f32_e32 v103, v103
	ds_read_b128 v[166:169], v133 offset:23040
	ds_read_b128 v[170:173], v133 offset:23072
	v_mfma_f32_32x32x16_bf16 v[80:95], v[174:177], v[158:161], v[80:95]
	v_exp_f32_e32 v104, v104
	v_exp_f32_e32 v105, v105
	v_add_f32_e32 v141, v141, v96
	v_add_f32_e32 v150, v150, v97
	v_add_f32_e32 v141, v141, v98
	v_add_f32_e32 v150, v150, v99
	v_mfma_f32_32x32x16_bf16 v[16:31], v[182:185], v[158:161], v[16:31]
	v_exp_f32_e32 v106, v106
	v_exp_f32_e32 v107, v107
	v_cvt_pk_bf16_f32 v158, v96, v97
	v_cvt_pk_bf16_f32 v159, v98, v99
	v_add_f32_e32 v141, v141, v100
	v_add_f32_e32 v150, v150, v101
	v_mfma_f32_32x32x16_bf16 v[80:95], v[178:181], v[162:165], v[80:95]
	v_exp_f32_e32 v108, v108
	v_exp_f32_e32 v109, v109
	v_cvt_pk_bf16_f32 v160, v100, v101
	v_cvt_pk_bf16_f32 v161, v102, v103
	v_add_f32_e32 v141, v141, v102
	v_add_f32_e32 v150, v150, v103
	v_mfma_f32_32x32x16_bf16 v[16:31], v[186:189], v[162:165], v[16:31]
	ds_read_b128 v[174:177], v133 offset:27648
	ds_read_b128 v[178:181], v133 offset:27680
	ds_read_b128 v[182:185], v133 offset:32256
	ds_read_b128 v[186:189], v133 offset:32288
	v_exp_f32_e32 v110, v110
	v_exp_f32_e32 v111, v111
	v_add_f32_e32 v141, v141, v104
	v_add_f32_e32 v150, v150, v105
	v_add_f32_e32 v141, v141, v106
	v_add_f32_e32 v150, v150, v107
	v_add_f32_e32 v141, v141, v108
	v_add_f32_e32 v150, v150, v109
	v_cvt_pk_bf16_f32 v162, v104, v105
	v_cvt_pk_bf16_f32 v163, v106, v107
	v_cvt_pk_bf16_f32 v164, v108, v109
	v_add_f32_e32 v141, v141, v110
	v_add_f32_e32 v150, v150, v111
	v_cvt_pk_bf16_f32 v165, v110, v111
	s_waitcnt lgkmcnt(0)
	v_mfma_f32_32x32x16_bf16 v[96:111], v[166:169], v[112:115], v[48:63]
	v_exp_f32_e32 v116, v116
	v_exp_f32_e32 v117, v117
	v_exp_f32_e32 v118, v118
	v_exp_f32_e32 v119, v119
	v_mfma_f32_32x32x16_bf16 v[96:111], v[170:173], v[42:45], v[96:111]
	v_exp_f32_e32 v120, v120
	v_exp_f32_e32 v121, v121
	v_exp_f32_e32 v122, v122
	v_exp_f32_e32 v123, v123
	ds_read_b128 v[166:169], v133 offset:23104
	ds_read_b128 v[170:173], v133 offset:23136
	v_mfma_f32_32x32x16_bf16 v[64:79], v[174:177], v[158:161], v[64:79]
	v_exp_f32_e32 v124, v124
	v_exp_f32_e32 v125, v125
	v_add_f32_e32 v140, v140, v116
	v_add_f32_e32 v151, v151, v117
	v_add_f32_e32 v140, v140, v118
	v_add_f32_e32 v151, v151, v119
	v_mfma_f32_32x32x16_bf16 v[0:15], v[182:185], v[158:161], v[0:15]
	v_exp_f32_e32 v126, v126
	v_exp_f32_e32 v127, v127
	v_cvt_pk_bf16_f32 v158, v116, v117
	v_cvt_pk_bf16_f32 v159, v118, v119
	v_add_f32_e32 v140, v140, v120
	v_add_f32_e32 v151, v151, v121
	v_mfma_f32_32x32x16_bf16 v[64:79], v[178:181], v[162:165], v[64:79]
	v_exp_f32_e32 v128, v128
	v_exp_f32_e32 v129, v129
	v_cvt_pk_bf16_f32 v160, v120, v121
	v_cvt_pk_bf16_f32 v161, v122, v123
	v_add_f32_e32 v140, v140, v122
	v_add_f32_e32 v151, v151, v123
	v_mfma_f32_32x32x16_bf16 v[0:15], v[186:189], v[162:165], v[0:15]
	v_exp_f32_e32 v130, v130
	v_exp_f32_e32 v131, v131
	v_add_f32_e32 v140, v140, v124
	v_add_f32_e32 v151, v151, v125
	v_add_f32_e32 v140, v140, v126
	v_add_f32_e32 v151, v151, v127
	v_add_f32_e32 v140, v140, v128
	v_add_f32_e32 v151, v151, v129
	v_cvt_pk_bf16_f32 v162, v124, v125
	v_cvt_pk_bf16_f32 v163, v126, v127
	v_cvt_pk_bf16_f32 v164, v128, v129
	v_add_f32_e32 v140, v140, v130
	v_add_f32_e32 v151, v151, v131
	v_cvt_pk_bf16_f32 v165, v130, v131
	s_waitcnt lgkmcnt(0)
; DI float ex2(float x) { return __builtin_amdgcn_exp2f(x); }
; #define MFMA32(a, b, c) __builtin_amdgcn_mfma_f32_32x32x16_bf16((a), (b), (c), 0, 0, 0)
; template <int MODE>
; DI void attn_unit(unsigned char* lds, const AttnParams& ap, int b, int h, int qb, int tid) {
;     ...
;     for (int c = 0; c < NCH; ++c) { *(u32x4*)(Ks0 + (c * 64 + lrow) * 72 + 8 * lch) = kreg[c]; *(u32x4*)(Vs0 + (c * 64 + lrow) * 72 + 8 * lch) = vreg[c]; }
;     __syncthreads();
;     if (n + NCH < ntiles) {
; #pragma unroll
;       for (int c = 0; c < NCH; ++c) { const int jn = (MODE == 2) ? jb - NCH - c : jb + NCH + c; kreg[c] = *(const u32x4*)(kg + (size_t)jn * 64 * PLD); vreg[c] = *(const u32x4*)(vg + (size_t)jn * 4096); } }
; #pragma unroll
;     for (int c = 0; c < NCH; ++c) {
;     const int j = (MODE == 2) ? jb - c : jb + c;
;     const bf16_t* Ks = Ks0 + c * 64 * 72; const bf16_t* Vs = Vs0 + c * 64 * 72;
;     const bool active = (j <= cw) && (MODE != 0 || j >= cw - 8);
;     if (!active) continue;
;     if (MODE == 2 && D_EARLY && wdone) continue;
;     if (MODE == 1) {
; #pragma unroll
;       for (int kh = 0; kh < 2; ++kh) {
;         const bf16_t* kb = Ks + (32 * kh + r32) * 72 + 8 * hi;
;         bf16x8 p0[2], p1[2];
;         { f32x16 s0 = splat16(ap.negM);
;           s0 = MFMA32(*(const bf16x8*)(kb), qf[0], s0); s0 = MFMA32(*(const bf16x8*)(kb + 16), qf[1], s0);
; #pragma unroll
;           for (int i = 0; i < 16; ++i) { s0[i] = ex2(s0[i]); l0 += s0[i]; }
;           p0[0] = pack8(s0, 0); p0[1] = pack8(s0, 1); }
;         { f32x16 s1 = splat16(ap.negM);
;           s1 = MFMA32(*(const bf16x8*)(kb + 32), qf[2], s1); s1 = MFMA32(*(const bf16x8*)(kb + 48), qf[3], s1);
; #pragma unroll
;           for (int i = 0; i < 16; ++i) { s1[i] = ex2(s1[i]); l1 += s1[i]; }
;           p1[0] = pack8(s1, 0); p1[1] = pack8(s1, 1); }
; #pragma unroll
;         for (int kk = 0; kk < 2; ++kk) {
; #pragma unroll
;           for (int eb = 0; eb < 2; ++eb) { const bf16_t* vb = Vs + (32 * eb + r32) * 72 + 32 * kh + 16 * kk + 8 * hi; const bf16x8 vf = *(const bf16x8*)vb;
;             O0[eb] = MFMA32(vf, p0[kk], O0[eb]); O1[eb] = MFMA32(vf, p1[kk], O1[eb]); } }
;       }
	v_mfma_f32_32x32x16_bf16 v[116:131], v[166:169], v[38:41], v[48:63]
	v_exp_f32_e32 v96, v96
	v_exp_f32_e32 v97, v97
	v_exp_f32_e32 v98, v98
	v_exp_f32_e32 v99, v99
	v_mfma_f32_32x32x16_bf16 v[116:131], v[170:173], v[34:37], v[116:131]
	v_exp_f32_e32 v100, v100
	v_exp_f32_e32 v101, v101
	v_exp_f32_e32 v102, v102
	v_exp_f32_e32 v103, v103
	ds_read_b128 v[166:169], v133 offset:36864
	ds_read_b128 v[170:173], v133 offset:36896
	v_mfma_f32_32x32x16_bf16 v[80:95], v[174:177], v[158:161], v[80:95]
	v_exp_f32_e32 v104, v104
	v_exp_f32_e32 v105, v105
	v_add_f32_e32 v141, v141, v96
	v_add_f32_e32 v150, v150, v97
	v_add_f32_e32 v141, v141, v98
	v_add_f32_e32 v150, v150, v99
	v_mfma_f32_32x32x16_bf16 v[16:31], v[182:185], v[158:161], v[16:31]
	v_exp_f32_e32 v106, v106
	v_exp_f32_e32 v107, v107
	v_cvt_pk_bf16_f32 v158, v96, v97
	v_cvt_pk_bf16_f32 v159, v98, v99
	v_add_f32_e32 v141, v141, v100
	v_add_f32_e32 v150, v150, v101
	v_mfma_f32_32x32x16_bf16 v[80:95], v[178:181], v[162:165], v[80:95]
	v_exp_f32_e32 v108, v108
	v_exp_f32_e32 v109, v109
	v_cvt_pk_bf16_f32 v160, v100, v101
	v_cvt_pk_bf16_f32 v161, v102, v103
	v_add_f32_e32 v141, v141, v102
	v_add_f32_e32 v150, v150, v103
	v_mfma_f32_32x32x16_bf16 v[16:31], v[186:189], v[162:165], v[16:31]
	ds_read_b128 v[174:177], v133 offset:27712
	ds_read_b128 v[178:181], v133 offset:27744
	ds_read_b128 v[182:185], v133 offset:32320
	ds_read_b128 v[186:189], v133 offset:32352
	v_exp_f32_e32 v110, v110
	v_exp_f32_e32 v111, v111
	v_add_f32_e32 v141, v141, v104
	v_add_f32_e32 v150, v150, v105
	v_add_f32_e32 v141, v141, v106
	v_add_f32_e32 v150, v150, v107
	v_add_f32_e32 v141, v141, v108
	v_add_f32_e32 v150, v150, v109
	v_cvt_pk_bf16_f32 v162, v104, v105
	v_cvt_pk_bf16_f32 v163, v106, v107
	v_cvt_pk_bf16_f32 v164, v108, v109
	v_add_f32_e32 v141, v141, v110
	v_add_f32_e32 v150, v150, v111
	v_cvt_pk_bf16_f32 v165, v110, v111
	s_waitcnt lgkmcnt(0)
	v_mfma_f32_32x32x16_bf16 v[96:111], v[166:169], v[112:115], v[48:63]
	v_exp_f32_e32 v116, v116
	v_exp_f32_e32 v117, v117
	v_exp_f32_e32 v118, v118
	v_exp_f32_e32 v119, v119
	v_mfma_f32_32x32x16_bf16 v[96:111], v[170:173], v[42:45], v[96:111]
	v_exp_f32_e32 v120, v120
	v_exp_f32_e32 v121, v121
	v_exp_f32_e32 v122, v122
	v_exp_f32_e32 v123, v123
	ds_read_b128 v[166:169], v133 offset:36928
	ds_read_b128 v[170:173], v133 offset:36960
	v_mfma_f32_32x32x16_bf16 v[64:79], v[174:177], v[158:161], v[64:79]
	v_exp_f32_e32 v124, v124
	v_exp_f32_e32 v125, v125
	v_add_f32_e32 v140, v140, v116
	v_add_f32_e32 v151, v151, v117
	v_add_f32_e32 v140, v140, v118
	v_add_f32_e32 v151, v151, v119
	v_mfma_f32_32x32x16_bf16 v[0:15], v[182:185], v[158:161], v[0:15]
	v_exp_f32_e32 v126, v126
	v_exp_f32_e32 v127, v127
	v_cvt_pk_bf16_f32 v158, v116, v117
	v_cvt_pk_bf16_f32 v159, v118, v119
	v_add_f32_e32 v140, v140, v120
	v_add_f32_e32 v151, v151, v121
	v_mfma_f32_32x32x16_bf16 v[64:79], v[178:181], v[162:165], v[64:79]
	v_exp_f32_e32 v128, v128
	v_exp_f32_e32 v129, v129
	v_cvt_pk_bf16_f32 v160, v120, v121
	v_cvt_pk_bf16_f32 v161, v122, v123
	v_add_f32_e32 v140, v140, v122
	v_add_f32_e32 v151, v151, v123
	v_mfma_f32_32x32x16_bf16 v[0:15], v[186:189], v[162:165], v[0:15]
	v_exp_f32_e32 v130, v130
	v_exp_f32_e32 v131, v131
	v_add_f32_e32 v140, v140, v124
	v_add_f32_e32 v151, v151, v125
	v_add_f32_e32 v140, v140, v126
	v_add_f32_e32 v151, v151, v127
	v_add_f32_e32 v140, v140, v128
	v_add_f32_e32 v151, v151, v129
	v_cvt_pk_bf16_f32 v162, v124, v125
	v_cvt_pk_bf16_f32 v163, v126, v127
	v_cvt_pk_bf16_f32 v164, v128, v129
	v_add_f32_e32 v140, v140, v130
	v_add_f32_e32 v151, v151, v131
	v_cvt_pk_bf16_f32 v165, v130, v131
	s_waitcnt vmcnt(0)
	ds_write_b128 v190, v[204:207]
	ds_write_b128 v190, v[142:145] offset:9216
	s_add_i32 s4, s4, 1
	s_waitcnt lgkmcnt(0)
	s_barrier
	s_nop 0
	s_barrier
	s_cmp_le_u32 s4, s5
	s_cbranch_scc1 .Lc_tile_ph2
	s_mov_b32 s9, 2
	s_branch .Lc_drain
.Lc_tile_ph2:
	global_load_dwordx4 v[204:207], v32, s[2:3]
	global_load_dwordx4 v[142:145], v157, s[10:11]
	s_add_u32 s2, s2, 0x68800
	s_addc_u32 s3, s3, 0
	s_add_u32 s10, s10, 0x2000
	s_addc_u32 s11, s11, 0
	s_waitcnt lgkmcnt(0)
	v_mfma_f32_32x32x16_bf16 v[116:131], v[166:169], v[38:41], v[48:63]
	v_exp_f32_e32 v96, v96
	v_exp_f32_e32 v97, v97
	v_exp_f32_e32 v98, v98
	v_exp_f32_e32 v99, v99
	v_mfma_f32_32x32x16_bf16 v[116:131], v[170:173], v[34:37], v[116:131]
	v_exp_f32_e32 v100, v100
	v_exp_f32_e32 v101, v101
	v_exp_f32_e32 v102, v102
	v_exp_f32_e32 v103, v103
	ds_read_b128 v[166:169], v133 offset:41472
	ds_read_b128 v[170:173], v133 offset:41504
	v_mfma_f32_32x32x16_bf16 v[80:95], v[174:177], v[158:161], v[80:95]
	v_exp_f32_e32 v104, v104
	v_exp_f32_e32 v105, v105
	v_add_f32_e32 v141, v141, v96
	v_add_f32_e32 v150, v150, v97
	v_add_f32_e32 v141, v141, v98
	v_add_f32_e32 v150, v150, v99
	v_mfma_f32_32x32x16_bf16 v[16:31], v[182:185], v[158:161], v[16:31]
	v_exp_f32_e32 v106, v106
	v_exp_f32_e32 v107, v107
	v_cvt_pk_bf16_f32 v158, v96, v97
	v_cvt_pk_bf16_f32 v159, v98, v99
	v_add_f32_e32 v141, v141, v100
	v_add_f32_e32 v150, v150, v101
	v_mfma_f32_32x32x16_bf16 v[80:95], v[178:181], v[162:165], v[80:95]
	v_exp_f32_e32 v108, v108
	v_exp_f32_e32 v109, v109
	v_cvt_pk_bf16_f32 v160, v100, v101
	v_cvt_pk_bf16_f32 v161, v102, v103
	v_add_f32_e32 v141, v141, v102
	v_add_f32_e32 v150, v150, v103
	v_mfma_f32_32x32x16_bf16 v[16:31], v[186:189], v[162:165], v[16:31]
	ds_read_b128 v[174:177], v133 offset:46080
	ds_read_b128 v[178:181], v133 offset:46112
	ds_read_b128 v[182:185], v133 offset:50688
	ds_read_b128 v[186:189], v133 offset:50720
	v_exp_f32_e32 v110, v110
	v_exp_f32_e32 v111, v111
	v_add_f32_e32 v141, v141, v104
	v_add_f32_e32 v150, v150, v105
	v_add_f32_e32 v141, v141, v106
	v_add_f32_e32 v150, v150, v107
	v_add_f32_e32 v141, v141, v108
	v_add_f32_e32 v150, v150, v109
	v_cvt_pk_bf16_f32 v162, v104, v105
	v_cvt_pk_bf16_f32 v163, v106, v107
	v_cvt_pk_bf16_f32 v164, v108, v109
	v_add_f32_e32 v141, v141, v110
	v_add_f32_e32 v150, v150, v111
	v_cvt_pk_bf16_f32 v165, v110, v111
	s_waitcnt lgkmcnt(0)
; DI float ex2(float x) { return __builtin_amdgcn_exp2f(x); }
; #define MFMA32(a, b, c) __builtin_amdgcn_mfma_f32_32x32x16_bf16((a), (b), (c), 0, 0, 0)
; template <int MODE>
; DI void attn_unit(unsigned char* lds, const AttnParams& ap, int b, int h, int qb, int tid) {
;     ...
;     for (int c = 0; c < NCH; ++c) { *(u32x4*)(Ks0 + (c * 64 + lrow) * 72 + 8 * lch) = kreg[c]; *(u32x4*)(Vs0 + (c * 64 + lrow) * 72 + 8 * lch) = vreg[c]; }
;     __syncthreads();
;     if (n + NCH < ntiles) {
; #pragma unroll
;       for (int c = 0; c < NCH; ++c) { const int jn = (MODE == 2) ? jb - NCH - c : jb + NCH + c; kreg[c] = *(const u32x4*)(kg + (size_t)jn * 64 * PLD); vreg[c] = *(const u32x4*)(vg + (size_t)jn * 4096); } }
; #pragma unroll
;     for (int c = 0; c < NCH; ++c) {
;     const int j = (MODE == 2) ? jb - c : jb + c;
;     const bf16_t* Ks = Ks0 + c * 64 * 72; const bf16_t* Vs = Vs0 + c * 64 * 72;
;     const bool active = (j <= cw) && (MODE != 0 || j >= cw - 8);
;     if (!active) continue;
;     if (MODE == 2 && D_EARLY && wdone) continue;
;     if (MODE == 1) {
; #pragma unroll
;       for (int kh = 0; kh < 2; ++kh) {
;         const bf16_t* kb = Ks + (32 * kh + r32) * 72 + 8 * hi;
;         bf16x8 p0[2], p1[2];
;         { f32x16 s0 = splat16(ap.negM);
;           s0 = MFMA32(*(const bf16x8*)(kb), qf[0], s0); s0 = MFMA32(*(const bf16x8*)(kb + 16), qf[1], s0);
; #pragma unroll
;           for (int i = 0; i < 16; ++i) { s0[i] = ex2(s0[i]); l0 += s0[i]; }
;           p0[0] = pack8(s0, 0); p0[1] = pack8(s0, 1); }
;         { f32x16 s1 = splat16(ap.negM);
;           s1 = MFMA32(*(const bf16x8*)(kb + 32), qf[2], s1); s1 = MFMA32(*(const bf16x8*)(kb + 48), qf[3], s1);
; #pragma unroll
;           for (int i = 0; i < 16; ++i) { s1[i] = ex2(s1[i]); l1 += s1[i]; }
;           p1[0] = pack8(s1, 0); p1[1] = pack8(s1, 1); }
; #pragma unroll
;         for (int kk = 0; kk < 2; ++kk) {
; #pragma unroll
;           for (int eb = 0; eb < 2; ++eb) { const bf16_t* vb = Vs + (32 * eb + r32) * 72 + 32 * kh + 16 * kk + 8 * hi; const bf16x8 vf = *(const bf16x8*)vb;
;             O0[eb] = MFMA32(vf, p0[kk], O0[eb]); O1[eb] = MFMA32(vf, p1[kk], O1[eb]); } }
;       }
	v_mfma_f32_32x32x16_bf16 v[96:111], v[166:169], v[112:115], v[48:63]
	v_exp_f32_e32 v116, v116
	v_exp_f32_e32 v117, v117
	v_exp_f32_e32 v118, v118
	v_exp_f32_e32 v119, v119
	v_mfma_f32_32x32x16_bf16 v[96:111], v[170:173], v[42:45], v[96:111]
	v_exp_f32_e32 v120, v120
	v_exp_f32_e32 v121, v121
	v_exp_f32_e32 v122, v122
	v_exp_f32_e32 v123, v123
	ds_read_b128 v[166:169], v133 offset:41536
	ds_read_b128 v[170:173], v133 offset:41568
	v_mfma_f32_32x32x16_bf16 v[64:79], v[174:177], v[158:161], v[64:79]
	v_exp_f32_e32 v124, v124
	v_exp_f32_e32 v125, v125
	v_add_f32_e32 v140, v140, v116
	v_add_f32_e32 v151, v151, v117
	v_add_f32_e32 v140, v140, v118
	v_add_f32_e32 v151, v151, v119
	v_mfma_f32_32x32x16_bf16 v[0:15], v[182:185], v[158:161], v[0:15]
	v_exp_f32_e32 v126, v126
	v_exp_f32_e32 v127, v127
	v_cvt_pk_bf16_f32 v158, v116, v117
	v_cvt_pk_bf16_f32 v159, v118, v119
	v_add_f32_e32 v140, v140, v120
	v_add_f32_e32 v151, v151, v121
	v_mfma_f32_32x32x16_bf16 v[64:79], v[178:181], v[162:165], v[64:79]
	v_exp_f32_e32 v128, v128
	v_exp_f32_e32 v129, v129
	v_cvt_pk_bf16_f32 v160, v120, v121
	v_cvt_pk_bf16_f32 v161, v122, v123
	v_add_f32_e32 v140, v140, v122
	v_add_f32_e32 v151, v151, v123
	v_mfma_f32_32x32x16_bf16 v[0:15], v[186:189], v[162:165], v[0:15]
	v_exp_f32_e32 v130, v130
	v_exp_f32_e32 v131, v131
	v_add_f32_e32 v140, v140, v124
	v_add_f32_e32 v151, v151, v125
	v_add_f32_e32 v140, v140, v126
	v_add_f32_e32 v151, v151, v127
	v_add_f32_e32 v140, v140, v128
	v_add_f32_e32 v151, v151, v129
	v_cvt_pk_bf16_f32 v162, v124, v125
	v_cvt_pk_bf16_f32 v163, v126, v127
	v_cvt_pk_bf16_f32 v164, v128, v129
	v_add_f32_e32 v140, v140, v130
	v_add_f32_e32 v151, v151, v131
	v_cvt_pk_bf16_f32 v165, v130, v131
	s_waitcnt lgkmcnt(0)
	v_mfma_f32_32x32x16_bf16 v[116:131], v[166:169], v[38:41], v[48:63]
	v_exp_f32_e32 v96, v96
	v_exp_f32_e32 v97, v97
	v_exp_f32_e32 v98, v98
	v_exp_f32_e32 v99, v99
	v_mfma_f32_32x32x16_bf16 v[116:131], v[170:173], v[34:37], v[116:131]
	v_exp_f32_e32 v100, v100
	v_exp_f32_e32 v101, v101
	v_exp_f32_e32 v102, v102
	v_exp_f32_e32 v103, v103
	ds_read_b128 v[166:169], v133
	ds_read_b128 v[170:173], v133 offset:32
	v_mfma_f32_32x32x16_bf16 v[80:95], v[174:177], v[158:161], v[80:95]
	v_exp_f32_e32 v104, v104
	v_exp_f32_e32 v105, v105
	v_add_f32_e32 v141, v141, v96
	v_add_f32_e32 v150, v150, v97
	v_add_f32_e32 v141, v141, v98
	v_add_f32_e32 v150, v150, v99
	v_mfma_f32_32x32x16_bf16 v[16:31], v[182:185], v[158:161], v[16:31]
	v_exp_f32_e32 v106, v106
	v_exp_f32_e32 v107, v107
	v_cvt_pk_bf16_f32 v158, v96, v97
	v_cvt_pk_bf16_f32 v159, v98, v99
	v_add_f32_e32 v141, v141, v100
	v_add_f32_e32 v150, v150, v101
	v_mfma_f32_32x32x16_bf16 v[80:95], v[178:181], v[162:165], v[80:95]
	v_exp_f32_e32 v108, v108
	v_exp_f32_e32 v109, v109
	v_cvt_pk_bf16_f32 v160, v100, v101
	v_cvt_pk_bf16_f32 v161, v102, v103
	v_add_f32_e32 v141, v141, v102
	v_add_f32_e32 v150, v150, v103
	v_mfma_f32_32x32x16_bf16 v[16:31], v[186:189], v[162:165], v[16:31]
	ds_read_b128 v[174:177], v133 offset:46144
	ds_read_b128 v[178:181], v133 offset:46176
	ds_read_b128 v[182:185], v133 offset:50752
	ds_read_b128 v[186:189], v133 offset:50784
	v_exp_f32_e32 v110, v110
	v_exp_f32_e32 v111, v111
	v_add_f32_e32 v141, v141, v104
	v_add_f32_e32 v150, v150, v105
	v_add_f32_e32 v141, v141, v106
	v_add_f32_e32 v150, v150, v107
	v_add_f32_e32 v141, v141, v108
	v_add_f32_e32 v150, v150, v109
	v_cvt_pk_bf16_f32 v162, v104, v105
	v_cvt_pk_bf16_f32 v163, v106, v107
	v_cvt_pk_bf16_f32 v164, v108, v109
	v_add_f32_e32 v141, v141, v110
	v_add_f32_e32 v150, v150, v111
	v_cvt_pk_bf16_f32 v165, v110, v111
	s_waitcnt lgkmcnt(0)
	v_mfma_f32_32x32x16_bf16 v[96:111], v[166:169], v[112:115], v[48:63]
	v_exp_f32_e32 v116, v116
	v_exp_f32_e32 v117, v117
	v_exp_f32_e32 v118, v118
	v_exp_f32_e32 v119, v119
	v_mfma_f32_32x32x16_bf16 v[96:111], v[170:173], v[42:45], v[96:111]
	v_exp_f32_e32 v120, v120
	v_exp_f32_e32 v121, v121
	v_exp_f32_e32 v122, v122
	v_exp_f32_e32 v123, v123
	ds_read_b128 v[166:169], v133 offset:64
	ds_read_b128 v[170:173], v133 offset:96
	v_mfma_f32_32x32x16_bf16 v[64:79], v[174:177], v[158:161], v[64:79]
	v_exp_f32_e32 v124, v124
	v_exp_f32_e32 v125, v125
	v_add_f32_e32 v140, v140, v116
	v_add_f32_e32 v151, v151, v117
	v_add_f32_e32 v140, v140, v118
	v_add_f32_e32 v151, v151, v119
	v_mfma_f32_32x32x16_bf16 v[0:15], v[182:185], v[158:161], v[0:15]
	v_exp_f32_e32 v126, v126
	v_exp_f32_e32 v127, v127
	v_cvt_pk_bf16_f32 v158, v116, v117
	v_cvt_pk_bf16_f32 v159, v118, v119
	v_add_f32_e32 v140, v140, v120
	v_add_f32_e32 v151, v151, v121
	v_mfma_f32_32x32x16_bf16 v[64:79], v[178:181], v[162:165], v[64:79]
	v_exp_f32_e32 v128, v128
	v_exp_f32_e32 v129, v129
	v_cvt_pk_bf16_f32 v160, v120, v121
	v_cvt_pk_bf16_f32 v161, v122, v123
	v_add_f32_e32 v140, v140, v122
	v_add_f32_e32 v151, v151, v123
	v_mfma_f32_32x32x16_bf16 v[0:15], v[186:189], v[162:165], v[0:15]
	v_exp_f32_e32 v130, v130
	v_exp_f32_e32 v131, v131
	v_add_f32_e32 v140, v140, v124
	v_add_f32_e32 v151, v151, v125
	v_add_f32_e32 v140, v140, v126
	v_add_f32_e32 v151, v151, v127
	v_add_f32_e32 v140, v140, v128
	v_add_f32_e32 v151, v151, v129
	v_cvt_pk_bf16_f32 v162, v124, v125
	v_cvt_pk_bf16_f32 v163, v126, v127
	v_cvt_pk_bf16_f32 v164, v128, v129
	v_add_f32_e32 v140, v140, v130
	v_add_f32_e32 v151, v151, v131
	v_cvt_pk_bf16_f32 v165, v130, v131
	s_waitcnt vmcnt(0)
	ds_write_b128 v190, v[204:207] offset:18432
	ds_write_b128 v190, v[142:145] offset:27648
	s_add_i32 s4, s4, 1
	s_waitcnt lgkmcnt(0)
	s_barrier
	s_nop 0
	s_barrier
	s_cmp_le_u32 s4, s5
	s_cbranch_scc1 .Lc_tile_ph0
	s_mov_b32 s9, 0
; template <int MODE>
; DI void attn_unit(unsigned char* lds, const AttnParams& ap, int b, int h, int qb, int tid) {
;     ...
;   for (int n = 0; n < ntiles; n += NCH) {
;     const int jb = (MODE == 2) ? jhi - n : jlo + n;
;     __syncthreads();
;     if (MODE == 2 && D_EARLY) { int alld = 1;
; #pragma unroll
;       for (int w = 0; w < 8; ++w) alld &= flags[w];
;       if (alld) break; }
; #pragma unroll
;     for (int c = 0; c < NCH; ++c) { *(u32x4*)(Ks0 + (c * 64 + lrow) * 72 + 8 * lch) = kreg[c]; *(u32x4*)(Vs0 + (c * 64 + lrow) * 72 + 8 * lch) = vreg[c]; }
;     __syncthreads();
;     if (n + NCH < ntiles) {
; #pragma unroll
;       for (int c = 0; c < NCH; ++c) { const int jn = (MODE == 2) ? jb - NCH - c : jb + NCH + c; kreg[c] = *(const u32x4*)(kg + (size_t)jn * 64 * PLD); vreg[c] = *(const u32x4*)(vg + (size_t)jn * 4096); } }
.Lc_drain:
	v_mfma_f32_32x32x16_bf16 v[80:95], v[174:177], v[158:161], v[80:95]
	v_mfma_f32_32x32x16_bf16 v[16:31], v[182:185], v[158:161], v[16:31]
	v_mfma_f32_32x32x16_bf16 v[80:95], v[178:181], v[162:165], v[80:95]
	v_mfma_f32_32x32x16_bf16 v[16:31], v[186:189], v[162:165], v[16:31]
	s_cmp_gt_u32 s4, s8
	s_cbranch_scc1 .Lc_tiles_done
	s_cmp_eq_u32 s9, 1
	s_cbranch_scc1 .Lc_idle_ph1
	s_cmp_eq_u32 s9, 2
	s_cbranch_scc1 .Lc_idle_ph2
.Lc_idle_ph0:
	global_load_dwordx4 v[204:207], v32, s[2:3]
	global_load_dwordx4 v[142:145], v157, s[10:11]
	s_add_u32 s2, s2, 0x68800
	s_addc_u32 s3, s3, 0
	s_add_u32 s10, s10, 0x2000
	s_addc_u32 s11, s11, 0
	s_waitcnt vmcnt(0)
	ds_write_b128 v190, v[204:207] offset:36864
	ds_write_b128 v190, v[142:145] offset:46080
	s_add_i32 s4, s4, 1
	s_waitcnt lgkmcnt(0)
	s_barrier
	s_nop 0
	s_barrier
	s_cmp_gt_u32 s4, s8
	s_cbranch_scc1 .Lc_tiles_done
.Lc_idle_ph1:
	global_load_dwordx4 v[204:207], v32, s[2:3]
	global_load_dwordx4 v[142:145], v157, s[10:11]
	s_add_u32 s2, s2, 0x68800
	s_addc_u32 s3, s3, 0
	s_add_u32 s10, s10, 0x2000
	s_addc_u32 s11, s11, 0
	s_waitcnt vmcnt(0)
	ds_write_b128 v190, v[204:207]
	ds_write_b128 v190, v[142:145] offset:9216
	s_add_i32 s4, s4, 1
	s_waitcnt lgkmcnt(0)
	s_barrier
	s_nop 0
	s_barrier
	s_cmp_gt_u32 s4, s8
	s_cbranch_scc1 .Lc_tiles_done
.Lc_idle_ph2:
	global_load_dwordx4 v[204:207], v32, s[2:3]
	global_load_dwordx4 v[142:145], v157, s[10:11]
	s_add_u32 s2, s2, 0x68800
	s_addc_u32 s3, s3, 0
	s_add_u32 s10, s10, 0x2000
	s_addc_u32 s11, s11, 0
	s_waitcnt vmcnt(0)
	ds_write_b128 v190, v[204:207] offset:18432
	ds_write_b128 v190, v[142:145] offset:27648
	s_add_i32 s4, s4, 1
	s_waitcnt lgkmcnt(0)
	s_barrier
	s_nop 0
	s_barrier
	s_cmp_gt_u32 s4, s8
	s_cbranch_scc1 .Lc_tiles_done
	s_branch .Lc_idle_ph0
